# v120 + tile heads test the band first (off-band tiles skip the per-wave tile-skip test and the s81 write; hand-over trampolines set s81)
# baseline (speedup 1.0000x reference)
; #define ATT_LAS __attribute__((address_space(3)))
; __device__ __forceinline__ void attn_unit(ATT_LAS unsigned char* lds, const bf16_t* Qg, const bf16_t* Kg, const bf16_t* Vg, bf16_t* Og, int b, int head, int qb, float lam, const float* subg) {
;     ...
;         const int kvrel = 64 * t - q0 - 32 * wq;
;         if (kvrel <= 31) {
;             const ATT_LAS unsigned char* kb = lds + KBUF + buf * 16384;
;             const ATT_LAS unsigned char* vb = lds + VBUF + buf * 16384;
;             tile_body(kvrel + 63 > 0, kb, vb, qbase, kaddr, vaddr, O1, O2, m1, m2, l1, l2, kvrel, r, h, wsf);
.Ltile_p0:
	s_cmpk_gt_i32 s80, 0xffc1
	s_cbranch_scc0 .Lfast_p0
	s_cmp_gt_i32 s80, 31
	s_cbranch_scc1 .Ldma_skip
	s_mov_b32 s81, 0x0

; #define ATT_LAS __attribute__((address_space(3)))
; __device__ __forceinline__ void attn_unit(ATT_LAS unsigned char* lds, const bf16_t* Qg, const bf16_t* Kg, const bf16_t* Vg, bf16_t* Og, int b, int head, int qb, float lam, const float* subg) {
;     ...
;         const int kvrel = 64 * t - q0 - 32 * wq;
;         if (kvrel <= 31) {
;             const ATT_LAS unsigned char* kb = lds + KBUF + buf * 16384;
;             const ATT_LAS unsigned char* vb = lds + VBUF + buf * 16384;
;             tile_body(kvrel + 63 > 0, kb, vb, qbase, kaddr, vaddr, O1, O2, m1, m2, l1, l2, kvrel, r, h, wsf);
.Ltile_p1:
	s_cmpk_gt_i32 s80, 0xffc1
	s_cbranch_scc0 .Lfast_p1
	s_cmp_gt_i32 s80, 31
	s_cbranch_scc1 .Ldma_skip
	s_mov_b32 s81, 0x4000

; __device__ __forceinline__ void tile_body(bool MASK, const ATT_LAS unsigned char* kb, const ATT_LAS unsigned char* vb, const ATT_LAS unsigned char* qbase, const int (&kaddr)[4], const int (&vaddr)[2], ...
;     ...
;     apply_mask(MASK, Sa, kvrel, r, h); ls = l1;
;     sm = step_fused<false, true, true>(Sa, m1, l1, pkA, O1, pkA, vb, vaddr, Sb, kb, qbase, kaddr);
;     if (__any(!(sm <= GUARD))) slow_step<false>(MASK, Sa, kb, qbase, kaddr, vaddr, O1, m1, l1, ls, kvrel, r, h, wsf, pkA);
.Ltramp_slow_1_p0:
	s_mov_b32 s81, 0x0
	s_mov_b64 s[36:37], 0
	s_mov_b64 s[4:5], exec
	s_branch .Lfix_slow_1

; __device__ __forceinline__ void tile_body(bool MASK, const ATT_LAS unsigned char* kb, const ATT_LAS unsigned char* vb, const ATT_LAS unsigned char* qbase, const int (&kaddr)[4], const int (&vaddr)[2], ...
;     ...
;     apply_mask(MASK, Sa, kvrel, r, h); ls = l1;
;     sm = step_fused<false, true, true>(Sa, m1, l1, pkA, O1, pkA, vb, vaddr, Sb, kb, qbase, kaddr);
;     if (__any(!(sm <= GUARD))) slow_step<false>(MASK, Sa, kb, qbase, kaddr, vaddr, O1, m1, l1, ls, kvrel, r, h, wsf, pkA);
.Ltramp_slow_1_p1:
	s_mov_b32 s81, 0x4000
	s_mov_b64 s[36:37], 0
	s_mov_b64 s[4:5], exec
	s_branch .Lfix_slow_1
